# grid barrier: each workgroup issues its cache invalidate right behind its arrival atomic (overlapping the wait for the other workgroups) instead of after the release
# speedup vs baseline: 1.0341x; 1.0189x over previous
.LBB0_39:
	s_or_b64 exec, exec, s[20:21]
	v_cvt_f32_u32_e32 v5, v3
	s_waitcnt vmcnt(0)
	v_readfirstlane_b32 s8, v4
	v_sub_u32_e32 v4, 0, v3
	v_rcp_iflag_f32_e32 v5, v5
	v_add_u32_e32 v6, s8, v0
	v_mul_f32_e32 v5, 0x4f7ffffe, v5
	v_cvt_u32_f32_e32 v5, v5
	v_mul_lo_u32 v0, v4, v5
	v_mul_hi_u32 v0, v5, v0
	v_add_u32_e32 v0, v5, v0
	v_mul_hi_u32 v0, v6, v0
	v_mul_lo_u32 v4, v0, v3
	v_sub_u32_e32 v4, v6, v4
	v_add_u32_e32 v5, 1, v0
	v_cmp_ge_u32_e32 vcc, v4, v3
	s_nop 1
	v_cndmask_b32_e32 v0, v0, v5, vcc
	v_sub_u32_e32 v5, v4, v3
	v_cndmask_b32_e32 v4, v4, v5, vcc
	v_add_u32_e32 v5, 1, v0
	v_cmp_ge_u32_e32 vcc, v4, v3
	v_add_u32_e32 v4, 1, v6
	s_nop 0
	v_cndmask_b32_e32 v0, v0, v5, vcc
	v_mul_lo_u32 v5, v3, v0
	v_add_u32_e32 v3, v5, v3
	v_cmp_ne_u32_e32 vcc, v4, v3
	s_and_saveexec_b64 s[20:21], vcc
	s_xor_b64 s[20:21], exec, s[20:21]
	s_cbranch_execz .LBB0_53
	v_readlane_b32 s22, v254, 17
	v_readlane_b32 s23, v254, 18
	s_waitcnt lgkmcnt(0)
	s_nop 3
	buffer_inv sc1
	global_load_dword v2, v1, s[22:23] sc1
	s_waitcnt vmcnt(0)
	v_cmp_eq_u32_e32 vcc, v2, v0
	s_and_saveexec_b64 s[22:23], vcc
	s_cbranch_execz .LBB0_52
	s_mov_b32 s8, 1
	s_mov_b64 s[24:25], 0
	s_branch .LBB0_43

.LBB0_52:
	s_or_b64 exec, exec, s[22:23]
	s_waitcnt vmcnt(0)
	s_waitcnt vmcnt(0)

.Lbar_nowb:
	s_waitcnt lgkmcnt(0)
	s_waitcnt vmcnt(0)
	v_mbcnt_lo_u32_b32 v0, s20, 0
	v_mbcnt_hi_u32_b32 v0, s21, v0
	v_cmp_eq_u32_e32 vcc, 0, v0
	s_and_saveexec_b64 s[22:23], vcc
	s_cbranch_execz .LBB0_56
	s_bcnt1_i32_b64 s8, s[20:21]
	v_readlane_b32 s20, v254, 15
	v_mov_b32_e32 v3, s8
	v_readlane_b32 s21, v254, 16
	s_nop 4
	global_atomic_add v3, v1, v3, s[20:21] sc0
	buffer_inv sc1
.LBB0_56:
	s_or_b64 exec, exec, s[22:23]
	s_waitcnt vmcnt(1)
	v_readfirstlane_b32 s8, v3
	v_sub_u32_e32 v4, 0, v2
	v_readlane_b32 s20, v254, 17
	v_add_u32_e32 v3, s8, v0
	v_cvt_f32_u32_e32 v0, v2
	v_readlane_b32 s21, v254, 18
	s_mov_b64 s[22:23], -1
	v_rcp_iflag_f32_e32 v0, v0
	s_nop 0
	v_mul_f32_e32 v0, 0x4f7ffffe, v0
	v_cvt_u32_f32_e32 v0, v0
	v_mul_lo_u32 v4, v4, v0
	v_mul_hi_u32 v4, v0, v4
	v_add_u32_e32 v0, v0, v4
	v_mul_hi_u32 v0, v3, v0
	v_mul_lo_u32 v4, v0, v2
	v_sub_u32_e32 v4, v3, v4
	v_cmp_ge_u32_e32 vcc, v4, v2
	v_add_u32_e32 v5, 1, v0
	v_add_u32_e32 v3, 1, v3
	v_cndmask_b32_e32 v0, v0, v5, vcc
	v_sub_u32_e32 v5, v4, v2
	v_cndmask_b32_e32 v4, v4, v5, vcc
	v_cmp_ge_u32_e32 vcc, v4, v2
	v_add_u32_e32 v4, 1, v0
	s_nop 0
	v_cndmask_b32_e32 v0, v0, v4, vcc
	v_mul_lo_u32 v4, v2, v0
	v_add_u32_e32 v2, v4, v2
	v_cmp_ne_u32_e32 vcc, v3, v2
	v_mov_b64_e32 v[2:3], s[20:21]
	s_and_saveexec_b64 s[20:21], vcc
	s_cbranch_execz .LBB0_68
	v_readlane_b32 s22, v254, 17
	v_readlane_b32 s23, v254, 18
	s_mov_b64 s[24:25], 0
	s_nop 3
	global_load_dword v2, v1, s[22:23] sc1
	s_waitcnt vmcnt(0)
	v_cmp_eq_u32_e32 vcc, v2, v0
	s_and_saveexec_b64 s[22:23], vcc
	s_cbranch_execz .LBB0_67
	s_mov_b32 s8, 1
	s_branch .LBB0_60

.LBB0_70:
	s_or_b64 exec, exec, s[20:21]
	s_mov_b64 s[20:21], exec
	v_mbcnt_lo_u32_b32 v0, s20, 0
	v_mbcnt_hi_u32_b32 v0, s21, v0
	v_cmp_eq_u32_e32 vcc, 0, v0
	s_waitcnt vmcnt(0)
	s_and_saveexec_b64 s[22:23], vcc
	s_cbranch_execz .LBB0_72
	s_bcnt1_i32_b64 s8, s[20:21]
	v_readlane_b32 s20, v254, 13
	v_mov_b32_e32 v0, s8
	v_readlane_b32 s21, v254, 14
	s_nop 4
	global_atomic_add v1, v0, s[20:21]
